# write-through sc1 policy on GEMM epilogue stores (ffn1, ffn2, merge1, merge2, inproj generic): outputs not retained in XCD L2
# speedup vs baseline: 1.0363x; 1.0077x over previous
.LBB0_142:
	v_add_u32_e32 v75, s15, v72
	v_ashrrev_i32_e32 v77, 5, v75
	v_add_u32_e32 v76, s14, v77
	v_mad_u64_u32 v[78:79], s[16:17], v77, s48, v[148:149]
	v_ashrrev_i32_e32 v77, 31, v76
	v_lshlrev_b64 v[80:81], 12, v[76:77]
	v_lshlrev_b32_e32 v76, 1, v76
	v_ashrrev_i32_e32 v77, 31, v76
	v_lshl_add_u64 v[76:77], v[76:77], 2, s[22:23]
	global_load_dwordx2 v[100:101], v[76:77], off
	v_lshl_add_u64 v[98:99], v[64:65], 0, v[80:81]
	ds_read_b128 v[76:79], v78 offset:32768
	global_load_dwordx4 v[80:83], v[98:99], off
	global_load_dwordx4 v[86:89], v[66:67], off
	global_load_dwordx4 v[90:93], v[68:69], off
	global_load_dwordx4 v[94:97], v[70:71], off
	s_addk_i32 s15, 0x400
	s_cmpk_eq_i32 s15, 0x800
	s_waitcnt vmcnt(3)
	v_pk_add_f32 v[80:81], v[80:81], v[100:101] op_sel_hi:[1,0] neg_lo:[0,1] neg_hi:[0,1]
	s_nop 0
	v_pk_mul_f32 v[80:81], v[100:101], v[80:81] op_sel:[1,0]
	s_waitcnt vmcnt(0)
	v_pk_fma_f32 v[80:81], v[80:81], v[90:91], v[94:95]
	s_nop 0
	v_pk_mul_f32 v[80:81], v[80:81], s[54:55] op_sel_hi:[1,0]
	s_waitcnt lgkmcnt(0)
	v_pk_fma_f32 v[76:77], v[76:77], v[86:87], v[80:81]
	v_pk_add_f32 v[80:81], v[82:83], v[100:101] op_sel_hi:[1,0] neg_lo:[0,1] neg_hi:[0,1]
	s_nop 0
	v_pk_mul_f32 v[80:81], v[100:101], v[80:81] op_sel:[1,0]
	s_nop 0
	v_pk_fma_f32 v[80:81], v[80:81], v[92:93], v[96:97]
	s_nop 0
	v_pk_mul_f32 v[80:81], v[80:81], s[54:55] op_sel_hi:[1,0]
	s_nop 0
	v_pk_fma_f32 v[78:79], v[78:79], v[88:89], v[80:81]
	global_store_dwordx4 v[98:99], v[76:79], off sc1
	s_nop 1
	v_add_u32_e32 v76, 0x100, v75
	v_ashrrev_i32_e32 v77, 5, v76
	v_add_u32_e32 v76, s14, v77
	v_mad_u64_u32 v[78:79], s[16:17], v77, s48, v[148:149]
	v_ashrrev_i32_e32 v77, 31, v76
	v_lshlrev_b64 v[80:81], 12, v[76:77]
	v_lshlrev_b32_e32 v76, 1, v76
	v_ashrrev_i32_e32 v77, 31, v76
	v_lshl_add_u64 v[76:77], v[76:77], 2, s[22:23]
	global_load_dwordx2 v[100:101], v[76:77], off
	v_lshl_add_u64 v[98:99], v[64:65], 0, v[80:81]
	ds_read_b128 v[76:79], v78 offset:32768
	global_load_dwordx4 v[80:83], v[98:99], off
	global_load_dwordx4 v[86:89], v[66:67], off
	global_load_dwordx4 v[90:93], v[68:69], off
	global_load_dwordx4 v[94:97], v[70:71], off
	s_waitcnt vmcnt(3)
	v_pk_add_f32 v[80:81], v[80:81], v[100:101] op_sel_hi:[1,0] neg_lo:[0,1] neg_hi:[0,1]
	s_nop 0
	v_pk_mul_f32 v[80:81], v[100:101], v[80:81] op_sel:[1,0]
	s_waitcnt vmcnt(0)
	v_pk_fma_f32 v[80:81], v[80:81], v[90:91], v[94:95]
	s_nop 0
	v_pk_mul_f32 v[80:81], v[80:81], s[54:55] op_sel_hi:[1,0]
	s_waitcnt lgkmcnt(0)
	v_pk_fma_f32 v[76:77], v[76:77], v[86:87], v[80:81]
	v_pk_add_f32 v[80:81], v[82:83], v[100:101] op_sel_hi:[1,0] neg_lo:[0,1] neg_hi:[0,1]
	s_nop 0
	v_pk_mul_f32 v[80:81], v[100:101], v[80:81] op_sel:[1,0]
	s_nop 0
	v_pk_fma_f32 v[80:81], v[80:81], v[92:93], v[96:97]
	s_nop 0
	v_pk_mul_f32 v[80:81], v[80:81], s[54:55] op_sel_hi:[1,0]
	s_nop 0
	v_pk_fma_f32 v[78:79], v[78:79], v[88:89], v[80:81]
	global_store_dwordx4 v[98:99], v[76:79], off sc1
	s_nop 1
	v_add_u32_e32 v76, 0x200, v75
	v_ashrrev_i32_e32 v77, 5, v76
	v_add_u32_e32 v76, s14, v77
	v_mad_u64_u32 v[78:79], s[16:17], v77, s48, v[148:149]
	v_ashrrev_i32_e32 v77, 31, v76
	v_lshlrev_b64 v[80:81], 12, v[76:77]
	v_lshlrev_b32_e32 v76, 1, v76
	v_ashrrev_i32_e32 v77, 31, v76
	v_lshl_add_u64 v[76:77], v[76:77], 2, s[22:23]
	global_load_dwordx2 v[100:101], v[76:77], off
	v_lshl_add_u64 v[98:99], v[64:65], 0, v[80:81]
	ds_read_b128 v[76:79], v78 offset:32768
	global_load_dwordx4 v[80:83], v[98:99], off
	global_load_dwordx4 v[86:89], v[66:67], off
	global_load_dwordx4 v[90:93], v[68:69], off
	global_load_dwordx4 v[94:97], v[70:71], off
	v_add_u32_e32 v75, 0x300, v75
	v_ashrrev_i32_e32 v75, 5, v75
	s_waitcnt vmcnt(3)
	v_pk_add_f32 v[80:81], v[80:81], v[100:101] op_sel_hi:[1,0] neg_lo:[0,1] neg_hi:[0,1]
	s_nop 0
	v_pk_mul_f32 v[80:81], v[100:101], v[80:81] op_sel:[1,0]
	s_waitcnt vmcnt(0)
	v_pk_fma_f32 v[80:81], v[80:81], v[90:91], v[94:95]
	s_nop 0
	v_pk_mul_f32 v[80:81], v[80:81], s[54:55] op_sel_hi:[1,0]
	s_waitcnt lgkmcnt(0)
	v_pk_fma_f32 v[76:77], v[76:77], v[86:87], v[80:81]
	v_pk_add_f32 v[80:81], v[82:83], v[100:101] op_sel_hi:[1,0] neg_lo:[0,1] neg_hi:[0,1]
	s_nop 0
	v_pk_mul_f32 v[80:81], v[100:101], v[80:81] op_sel:[1,0]
	s_nop 0
	v_pk_fma_f32 v[80:81], v[80:81], v[92:93], v[96:97]
	s_nop 0
	v_pk_mul_f32 v[80:81], v[80:81], s[54:55] op_sel_hi:[1,0]
	s_nop 0
	v_pk_fma_f32 v[78:79], v[78:79], v[88:89], v[80:81]
	global_store_dwordx4 v[98:99], v[76:79], off sc1
	s_nop 1
	v_add_u32_e32 v76, s14, v75
	v_ashrrev_i32_e32 v77, 31, v76
	v_lshlrev_b64 v[80:81], 12, v[76:77]
	v_lshlrev_b32_e32 v76, 1, v76
	v_ashrrev_i32_e32 v77, 31, v76
	v_lshl_add_u64 v[76:77], v[76:77], 2, s[22:23]
	global_load_dwordx2 v[100:101], v[76:77], off
	v_mad_u64_u32 v[78:79], s[16:17], v75, s48, v[148:149]
	v_lshl_add_u64 v[98:99], v[64:65], 0, v[80:81]
	ds_read_b128 v[76:79], v78 offset:32768
	global_load_dwordx4 v[80:83], v[98:99], off
	global_load_dwordx4 v[86:89], v[66:67], off
	global_load_dwordx4 v[90:93], v[68:69], off
	global_load_dwordx4 v[94:97], v[70:71], off
	s_waitcnt vmcnt(3)
	v_pk_add_f32 v[80:81], v[80:81], v[100:101] op_sel_hi:[1,0] neg_lo:[0,1] neg_hi:[0,1]
	s_nop 0
	v_pk_mul_f32 v[80:81], v[100:101], v[80:81] op_sel:[1,0]
	s_waitcnt vmcnt(0)
	v_pk_fma_f32 v[80:81], v[80:81], v[90:91], v[94:95]
	s_nop 0
	v_pk_mul_f32 v[80:81], v[80:81], s[54:55] op_sel_hi:[1,0]
	s_waitcnt lgkmcnt(0)
	v_pk_fma_f32 v[76:77], v[76:77], v[86:87], v[80:81]
	v_pk_add_f32 v[80:81], v[82:83], v[100:101] op_sel_hi:[1,0] neg_lo:[0,1] neg_hi:[0,1]
	s_nop 0
	v_pk_mul_f32 v[80:81], v[100:101], v[80:81] op_sel:[1,0]
	s_nop 0
	v_pk_fma_f32 v[80:81], v[80:81], v[92:93], v[96:97]
	s_nop 0
	v_pk_mul_f32 v[80:81], v[80:81], s[54:55] op_sel_hi:[1,0]
	s_nop 0
	v_pk_fma_f32 v[78:79], v[78:79], v[88:89], v[80:81]
	global_store_dwordx4 v[98:99], v[76:79], off sc1
	s_cbranch_scc0 .LBB0_142
	s_mov_b32 s14, 1
	s_mov_b64 s[30:31], 0
	s_and_b64 vcc, exec, s[28:29]
	s_cbranch_vccz .LBB0_139
	s_mov_b64 s[22:23], -1
	s_and_b64 vcc, exec, s[6:7]
	s_mov_b32 s14, s56
	s_cbranch_vccz .LBB0_117

.LBB0_177:
	v_mov_b32_e32 v64, v254
	s_waitcnt vmcnt(0)
	s_barrier
	s_nop 1
	v_max_f32_e32 v0, v0, v0
	v_lshrrev_b32_e32 v66, 2, v64
	v_lshrrev_b32_e32 v65, 1, v64
	v_and_b32_e32 v66, 12, v66
	v_and_or_b32 v65, v65, s49, v66
	v_max_f32_e32 v0, 0, v0
	v_and_b32_e32 v64, 0x4f, v64
	v_mul_lo_u32 v65, v65, s42
	v_mul_f32_e32 v0, v0, v0
	v_lshl_add_u32 v64, v64, 1, v65
	v_cvt_pk_bf16_f32 v0, v0, s0
	ds_write_b16 v64, v0 offset:45856
	v_max_f32_e32 v0, v1, v1
	v_max_f32_e32 v0, 0, v0
	v_mul_f32_e32 v0, v0, v0
	v_cvt_pk_bf16_f32 v0, v0, s0
	ds_write_b16 v64, v0 offset:46128
	v_max_f32_e32 v0, v2, v2
	v_max_f32_e32 v0, 0, v0
	v_mul_f32_e32 v0, v0, v0
	v_cvt_pk_bf16_f32 v0, v0, s0
	ds_write_b16 v64, v0 offset:46400
	v_max_f32_e32 v0, v3, v3
	v_max_f32_e32 v0, 0, v0
	v_mul_f32_e32 v0, v0, v0
	v_cvt_pk_bf16_f32 v0, v0, s0
	ds_write_b16 v64, v0 offset:46672
	v_max_f32_e32 v0, v12, v12
	v_max_f32_e32 v0, 0, v0
	v_mul_f32_e32 v0, v0, v0
	v_cvt_pk_bf16_f32 v0, v0, s0
	ds_write_b16 v64, v0 offset:45888
	v_max_f32_e32 v0, v13, v13
	v_max_f32_e32 v0, 0, v0
	v_mul_f32_e32 v0, v0, v0
	v_cvt_pk_bf16_f32 v0, v0, s0
	ds_write_b16 v64, v0 offset:46160
	v_max_f32_e32 v0, v14, v14
	v_max_f32_e32 v0, 0, v0
	v_mul_f32_e32 v0, v0, v0
	v_cvt_pk_bf16_f32 v0, v0, s0
	ds_write_b16 v64, v0 offset:46432
	v_max_f32_e32 v0, v15, v15
	v_max_f32_e32 v0, 0, v0
	v_mul_f32_e32 v0, v0, v0
	v_cvt_pk_bf16_f32 v0, v0, s0
	v_max_f32_e32 v60, v60, v60
	v_max_f32_e32 v56, v56, v56
	v_max_f32_e32 v52, v52, v52
	v_max_f32_e32 v48, v48, v48
	v_max_f32_e32 v44, v44, v44
	v_max_f32_e32 v40, v40, v40
	v_max_f32_e32 v36, v36, v36
	v_max_f32_e32 v32, v32, v32
	v_max_f32_e32 v28, v28, v28
	v_max_f32_e32 v24, v24, v24
	v_max_f32_e32 v20, v20, v20
	v_max_f32_e32 v16, v16, v16
	v_max_f32_e32 v8, v8, v8
	ds_write_b16 v64, v0 offset:46704
	v_max_f32_e32 v0, v4, v4
	v_max_f32_e32 v60, 0, v60
	v_max_f32_e32 v56, 0, v56
	v_max_f32_e32 v52, 0, v52
	v_max_f32_e32 v48, 0, v48
	v_max_f32_e32 v44, 0, v44
	v_max_f32_e32 v40, 0, v40
	v_max_f32_e32 v36, 0, v36
	v_max_f32_e32 v32, 0, v32
	v_max_f32_e32 v28, 0, v28
	v_max_f32_e32 v24, 0, v24
	v_max_f32_e32 v20, 0, v20
	v_max_f32_e32 v16, 0, v16
	v_max_f32_e32 v8, 0, v8
	v_max_f32_e32 v0, 0, v0
	v_mul_f32_e32 v60, v60, v60
	v_mul_f32_e32 v56, v56, v56
	v_mul_f32_e32 v52, v52, v52
	v_mul_f32_e32 v48, v48, v48
	v_mul_f32_e32 v44, v44, v44
	v_mul_f32_e32 v40, v40, v40
	v_mul_f32_e32 v36, v36, v36
	v_mul_f32_e32 v32, v32, v32
	v_mul_f32_e32 v28, v28, v28
	v_mul_f32_e32 v24, v24, v24
	v_mul_f32_e32 v20, v20, v20
	v_mul_f32_e32 v16, v16, v16
	v_mul_f32_e32 v8, v8, v8
	v_mul_f32_e32 v0, v0, v0
	v_cvt_pk_bf16_f32 v60, v60, s0
	v_cvt_pk_bf16_f32 v56, v56, s0
	v_cvt_pk_bf16_f32 v52, v52, s0
	v_cvt_pk_bf16_f32 v48, v48, s0
	v_cvt_pk_bf16_f32 v44, v44, s0
	v_cvt_pk_bf16_f32 v40, v40, s0
	v_cvt_pk_bf16_f32 v36, v36, s0
	v_cvt_pk_bf16_f32 v32, v32, s0
	v_cvt_pk_bf16_f32 v28, v28, s0
	v_cvt_pk_bf16_f32 v24, v24, s0
	v_cvt_pk_bf16_f32 v20, v20, s0
	v_cvt_pk_bf16_f32 v16, v16, s0
	v_cvt_pk_bf16_f32 v8, v8, s0
	v_cvt_pk_bf16_f32 v0, v0, s0
	ds_write_b16 v64, v60 offset:32768
	v_max_f32_e32 v60, v61, v61
	ds_write_b16 v64, v56 offset:32800
	v_max_f32_e32 v56, v57, v57
	ds_write_b16 v64, v52 offset:32832
	v_max_f32_e32 v52, v53, v53
	ds_write_b16 v64, v48 offset:32864
	v_max_f32_e32 v48, v49, v49
	ds_write_b16 v64, v44 offset:37120
	v_max_f32_e32 v44, v45, v45
	ds_write_b16 v64, v40 offset:37152
	v_max_f32_e32 v40, v41, v41
	ds_write_b16 v64, v36 offset:37184
	v_max_f32_e32 v36, v37, v37
	ds_write_b16 v64, v32 offset:37216
	v_max_f32_e32 v32, v33, v33
	ds_write_b16 v64, v28 offset:41472
	v_max_f32_e32 v28, v29, v29
	ds_write_b16 v64, v24 offset:41504
	v_max_f32_e32 v24, v25, v25
	ds_write_b16 v64, v20 offset:41536
	v_max_f32_e32 v20, v21, v21
	ds_write_b16 v64, v16 offset:41568
	v_max_f32_e32 v16, v17, v17
	ds_write_b16 v64, v8 offset:45824
	v_max_f32_e32 v8, v9, v9
	ds_write_b16 v64, v0 offset:45920
	v_max_f32_e32 v0, v5, v5
	v_max_f32_e32 v60, 0, v60
	v_max_f32_e32 v56, 0, v56
	v_max_f32_e32 v52, 0, v52
	v_max_f32_e32 v48, 0, v48
	v_max_f32_e32 v44, 0, v44
	v_max_f32_e32 v40, 0, v40
	v_max_f32_e32 v36, 0, v36
	v_max_f32_e32 v32, 0, v32
	v_max_f32_e32 v28, 0, v28
	v_max_f32_e32 v24, 0, v24
	v_max_f32_e32 v20, 0, v20
	v_max_f32_e32 v16, 0, v16
	v_max_f32_e32 v8, 0, v8
	v_max_f32_e32 v0, 0, v0
	v_mul_f32_e32 v60, v60, v60
	v_mul_f32_e32 v56, v56, v56
	v_mul_f32_e32 v52, v52, v52
	v_mul_f32_e32 v48, v48, v48
	v_mul_f32_e32 v44, v44, v44
	v_mul_f32_e32 v40, v40, v40
	v_mul_f32_e32 v36, v36, v36
	v_mul_f32_e32 v32, v32, v32
	v_mul_f32_e32 v28, v28, v28
	v_mul_f32_e32 v24, v24, v24
	v_mul_f32_e32 v20, v20, v20
	v_mul_f32_e32 v16, v16, v16
	v_mul_f32_e32 v8, v8, v8
	v_mul_f32_e32 v0, v0, v0
	v_cvt_pk_bf16_f32 v60, v60, s0
	v_cvt_pk_bf16_f32 v56, v56, s0
	v_cvt_pk_bf16_f32 v52, v52, s0
	v_cvt_pk_bf16_f32 v48, v48, s0
	v_cvt_pk_bf16_f32 v44, v44, s0
	v_cvt_pk_bf16_f32 v40, v40, s0
	v_cvt_pk_bf16_f32 v36, v36, s0
	v_cvt_pk_bf16_f32 v32, v32, s0
	v_cvt_pk_bf16_f32 v28, v28, s0
	v_cvt_pk_bf16_f32 v24, v24, s0
	v_cvt_pk_bf16_f32 v20, v20, s0
	v_cvt_pk_bf16_f32 v16, v16, s0
	v_cvt_pk_bf16_f32 v8, v8, s0
	v_cvt_pk_bf16_f32 v0, v0, s0
	ds_write_b16 v64, v60 offset:33040
	v_max_f32_e32 v60, v62, v62
	ds_write_b16 v64, v56 offset:33072
	v_max_f32_e32 v56, v58, v58
	ds_write_b16 v64, v52 offset:33104
	v_max_f32_e32 v52, v54, v54
	ds_write_b16 v64, v48 offset:33136
	v_max_f32_e32 v48, v50, v50
	ds_write_b16 v64, v44 offset:37392
	v_max_f32_e32 v44, v46, v46
	ds_write_b16 v64, v40 offset:37424
	v_max_f32_e32 v40, v42, v42
	ds_write_b16 v64, v36 offset:37456
	v_max_f32_e32 v36, v38, v38
	ds_write_b16 v64, v32 offset:37488
	v_max_f32_e32 v32, v34, v34
	ds_write_b16 v64, v28 offset:41744
	v_max_f32_e32 v28, v30, v30
	ds_write_b16 v64, v24 offset:41776
	v_max_f32_e32 v24, v26, v26
	ds_write_b16 v64, v20 offset:41808
	v_max_f32_e32 v20, v22, v22
	ds_write_b16 v64, v16 offset:41840
	v_max_f32_e32 v16, v18, v18
	ds_write_b16 v64, v8 offset:46096
	v_max_f32_e32 v8, v10, v10
	ds_write_b16 v64, v0 offset:46192
	v_max_f32_e32 v0, v6, v6
	v_max_f32_e32 v60, 0, v60
	v_max_f32_e32 v56, 0, v56
	v_max_f32_e32 v52, 0, v52
	v_max_f32_e32 v48, 0, v48
	v_max_f32_e32 v44, 0, v44
	v_max_f32_e32 v40, 0, v40
	v_max_f32_e32 v36, 0, v36
	v_max_f32_e32 v32, 0, v32
	v_max_f32_e32 v28, 0, v28
	v_max_f32_e32 v24, 0, v24
	v_max_f32_e32 v20, 0, v20
	v_max_f32_e32 v16, 0, v16
	v_max_f32_e32 v8, 0, v8
	v_max_f32_e32 v0, 0, v0
	v_mul_f32_e32 v60, v60, v60
	v_mul_f32_e32 v56, v56, v56
	v_mul_f32_e32 v52, v52, v52
	v_mul_f32_e32 v48, v48, v48
	v_mul_f32_e32 v44, v44, v44
	v_mul_f32_e32 v40, v40, v40
	v_mul_f32_e32 v36, v36, v36
	v_mul_f32_e32 v32, v32, v32
	v_mul_f32_e32 v28, v28, v28
	v_mul_f32_e32 v24, v24, v24
	v_mul_f32_e32 v20, v20, v20
	v_mul_f32_e32 v16, v16, v16
	v_mul_f32_e32 v8, v8, v8
	v_mul_f32_e32 v0, v0, v0
	v_cvt_pk_bf16_f32 v60, v60, s0
	v_cvt_pk_bf16_f32 v56, v56, s0
	v_cvt_pk_bf16_f32 v52, v52, s0
	v_cvt_pk_bf16_f32 v48, v48, s0
	v_cvt_pk_bf16_f32 v44, v44, s0
	v_cvt_pk_bf16_f32 v40, v40, s0
	v_cvt_pk_bf16_f32 v36, v36, s0
	v_cvt_pk_bf16_f32 v32, v32, s0
	v_cvt_pk_bf16_f32 v28, v28, s0
	v_cvt_pk_bf16_f32 v24, v24, s0
	v_cvt_pk_bf16_f32 v20, v20, s0
	v_cvt_pk_bf16_f32 v16, v16, s0
	v_cvt_pk_bf16_f32 v8, v8, s0
	v_cvt_pk_bf16_f32 v0, v0, s0
	ds_write_b16 v64, v60 offset:33312
	v_max_f32_e32 v60, v63, v63
	ds_write_b16 v64, v56 offset:33344
	v_max_f32_e32 v56, v59, v59
	ds_write_b16 v64, v52 offset:33376
	v_max_f32_e32 v52, v55, v55
	ds_write_b16 v64, v48 offset:33408
	v_max_f32_e32 v48, v51, v51
	ds_write_b16 v64, v44 offset:37664
	v_max_f32_e32 v44, v47, v47
	ds_write_b16 v64, v40 offset:37696
	v_max_f32_e32 v40, v43, v43
	ds_write_b16 v64, v36 offset:37728
	v_max_f32_e32 v36, v39, v39
	ds_write_b16 v64, v32 offset:37760
	v_max_f32_e32 v32, v35, v35
	ds_write_b16 v64, v28 offset:42016
	v_max_f32_e32 v28, v31, v31
	ds_write_b16 v64, v24 offset:42048
	v_max_f32_e32 v24, v27, v27
	ds_write_b16 v64, v20 offset:42080
	v_max_f32_e32 v20, v23, v23
	ds_write_b16 v64, v16 offset:42112
	v_max_f32_e32 v16, v19, v19
	ds_write_b16 v64, v8 offset:46368
	v_max_f32_e32 v8, v11, v11
	ds_write_b16 v64, v0 offset:46464
	v_max_f32_e32 v0, v7, v7
	s_lshl_b64 s[8:9], s[26:27], 13
	v_max_f32_e32 v60, 0, v60
	v_max_f32_e32 v56, 0, v56
	v_max_f32_e32 v52, 0, v52
	v_max_f32_e32 v48, 0, v48
	v_max_f32_e32 v44, 0, v44
	v_max_f32_e32 v40, 0, v40
	v_max_f32_e32 v36, 0, v36
	v_max_f32_e32 v32, 0, v32
	v_max_f32_e32 v28, 0, v28
	v_max_f32_e32 v24, 0, v24
	v_max_f32_e32 v20, 0, v20
	v_max_f32_e32 v16, 0, v16
	v_max_f32_e32 v8, 0, v8
	v_max_f32_e32 v0, 0, v0
	s_add_u32 s14, s44, s8
	v_mul_f32_e32 v60, v60, v60
	v_mul_f32_e32 v56, v56, v56
	v_mul_f32_e32 v52, v52, v52
	v_mul_f32_e32 v48, v48, v48
	v_mul_f32_e32 v44, v44, v44
	v_mul_f32_e32 v40, v40, v40
	v_mul_f32_e32 v36, v36, v36
	v_mul_f32_e32 v32, v32, v32
	v_mul_f32_e32 v28, v28, v28
	v_mul_f32_e32 v24, v24, v24
	v_mul_f32_e32 v20, v20, v20
	v_mul_f32_e32 v16, v16, v16
	v_mul_f32_e32 v8, v8, v8
	v_mul_f32_e32 v0, v0, v0
	s_addc_u32 s15, s45, s9
	s_lshl_b64 s[8:9], s[20:21], 1
	v_cvt_pk_bf16_f32 v60, v60, s0
	v_cvt_pk_bf16_f32 v56, v56, s0
	v_cvt_pk_bf16_f32 v52, v52, s0
	v_cvt_pk_bf16_f32 v48, v48, s0
	v_cvt_pk_bf16_f32 v44, v44, s0
	v_cvt_pk_bf16_f32 v40, v40, s0
	v_cvt_pk_bf16_f32 v36, v36, s0
	v_cvt_pk_bf16_f32 v32, v32, s0
	v_cvt_pk_bf16_f32 v28, v28, s0
	v_cvt_pk_bf16_f32 v24, v24, s0
	v_cvt_pk_bf16_f32 v20, v20, s0
	v_cvt_pk_bf16_f32 v16, v16, s0
	v_cvt_pk_bf16_f32 v8, v8, s0
	v_cvt_pk_bf16_f32 v0, v0, s0
	v_mov_b32_e32 v14, v254
	s_add_u32 s8, s14, s8
	ds_write_b16 v64, v60 offset:33584
	ds_write_b16 v64, v56 offset:33616
	ds_write_b16 v64, v52 offset:33648
	ds_write_b16 v64, v48 offset:33680
	ds_write_b16 v64, v44 offset:37936
	ds_write_b16 v64, v40 offset:37968
	ds_write_b16 v64, v36 offset:38000
	ds_write_b16 v64, v32 offset:38032
	ds_write_b16 v64, v28 offset:42288
	ds_write_b16 v64, v24 offset:42320
	ds_write_b16 v64, v20 offset:42352
	ds_write_b16 v64, v16 offset:42384
	ds_write_b16 v64, v8 offset:46640
	ds_write_b16 v64, v0 offset:46736
	s_waitcnt lgkmcnt(0)
	s_barrier
	s_addc_u32 s9, s15, s9
	v_lshlrev_b32_e32 v0, 4, v14
	v_ashrrev_i32_e32 v4, 4, v14
	v_and_b32_e32 v148, 0xf0, v0
	v_ashrrev_i32_e32 v5, 31, v4
	v_lshl_add_u64 v[8:9], s[8:9], 0, v[148:149]
	v_mad_u64_u32 v[0:1], s[8:9], v4, s42, v[148:149]
	v_lshlrev_b64 v[4:5], 13, v[4:5]
	v_lshl_add_u64 v[10:11], v[8:9], 0, v[4:5]
	v_add_u32_e32 v4, 0x100, v14
	ds_read_b128 v[0:3], v0 offset:32768
	v_ashrrev_i32_e32 v12, 4, v4
	v_mad_u64_u32 v[4:5], s[8:9], v12, s42, v[148:149]
	ds_read_b128 v[4:7], v4 offset:32768
	v_ashrrev_i32_e32 v13, 31, v12
	s_waitcnt lgkmcnt(1)
	global_store_dwordx4 v[10:11], v[0:3], off sc1
	s_and_b64 vcc, exec, s[6:7]
	s_mov_b32 s14, s46
	v_lshlrev_b64 v[0:1], 13, v[12:13]
	v_lshl_add_u64 v[0:1], v[8:9], 0, v[0:1]
	s_waitcnt lgkmcnt(0)
	global_store_dwordx4 v[0:1], v[4:7], off sc1
	v_add_u32_e32 v0, 0x200, v14
	s_nop 0
	v_ashrrev_i32_e32 v4, 4, v0
	v_ashrrev_i32_e32 v5, 31, v4
	v_mad_u64_u32 v[0:1], s[8:9], v4, s42, v[148:149]
	v_lshlrev_b64 v[4:5], 13, v[4:5]
	v_lshl_add_u64 v[10:11], v[8:9], 0, v[4:5]
	v_add_u32_e32 v4, 0x300, v14
	ds_read_b128 v[0:3], v0 offset:32768
	v_ashrrev_i32_e32 v12, 4, v4
	v_mad_u64_u32 v[4:5], s[8:9], v12, s42, v[148:149]
	ds_read_b128 v[4:7], v4 offset:32768
	v_ashrrev_i32_e32 v13, 31, v12
	s_waitcnt lgkmcnt(1)
	global_store_dwordx4 v[10:11], v[0:3], off sc1
	s_nop 1
	v_lshlrev_b64 v[0:1], 13, v[12:13]
	v_lshl_add_u64 v[0:1], v[8:9], 0, v[0:1]
	s_waitcnt lgkmcnt(0)
	global_store_dwordx4 v[0:1], v[4:7], off sc1
	v_add_u32_e32 v0, 0x400, v14
	s_nop 0
	v_ashrrev_i32_e32 v4, 4, v0
	v_ashrrev_i32_e32 v5, 31, v4
	v_mad_u64_u32 v[0:1], s[8:9], v4, s42, v[148:149]
	v_lshlrev_b64 v[4:5], 13, v[4:5]
	v_lshl_add_u64 v[10:11], v[8:9], 0, v[4:5]
	v_add_u32_e32 v4, 0x500, v14
	ds_read_b128 v[0:3], v0 offset:32768
	v_ashrrev_i32_e32 v12, 4, v4
	v_mad_u64_u32 v[4:5], s[8:9], v12, s42, v[148:149]
	ds_read_b128 v[4:7], v4 offset:32768
	v_ashrrev_i32_e32 v13, 31, v12
	s_waitcnt lgkmcnt(1)
	global_store_dwordx4 v[10:11], v[0:3], off sc1
	s_nop 1
	v_lshlrev_b64 v[0:1], 13, v[12:13]
	v_lshl_add_u64 v[0:1], v[8:9], 0, v[0:1]
	s_waitcnt lgkmcnt(0)
	global_store_dwordx4 v[0:1], v[4:7], off sc1
	v_add_u32_e32 v0, 0x600, v14
	s_nop 0
	v_ashrrev_i32_e32 v4, 4, v0
	v_ashrrev_i32_e32 v5, 31, v4
	v_mad_u64_u32 v[0:1], s[8:9], v4, s42, v[148:149]
	v_lshlrev_b64 v[4:5], 13, v[4:5]
	v_lshl_add_u64 v[10:11], v[8:9], 0, v[4:5]
	v_add_u32_e32 v4, 0x700, v14
	ds_read_b128 v[0:3], v0 offset:32768
	v_ashrrev_i32_e32 v12, 4, v4
	v_mad_u64_u32 v[4:5], s[8:9], v12, s42, v[148:149]
	ds_read_b128 v[4:7], v4 offset:32768
	v_ashrrev_i32_e32 v13, 31, v12
	s_waitcnt lgkmcnt(1)
	global_store_dwordx4 v[10:11], v[0:3], off sc1
	s_mov_b64 s[8:9], -1
	s_nop 0
	v_lshlrev_b64 v[0:1], 13, v[12:13]
	v_lshl_add_u64 v[0:1], v[8:9], 0, v[0:1]
	s_waitcnt lgkmcnt(0)
	global_store_dwordx4 v[0:1], v[4:7], off sc1
	s_cbranch_vccnz .LBB0_199

.LBB0_276:
	v_lshlrev_b64 v[86:87], 10, v[86:87]
	s_waitcnt vmcnt(1)
	v_pk_mul_f32 v[64:65], v[64:65], s[54:55] op_sel_hi:[1,0]
	v_pk_mul_f32 v[66:67], v[66:67], s[54:55] op_sel_hi:[1,0]
	s_addk_i32 s15, 0x400
	v_lshl_add_u64 v[86:87], v[86:87], 2, v[80:81]
	s_waitcnt vmcnt(0) lgkmcnt(0)
	v_pk_fma_f32 v[64:65], v[72:73], v[68:69], v[64:65]
	v_pk_fma_f32 v[66:67], v[74:75], v[70:71], v[66:67]
	s_cmpk_eq_i32 s15, 0x800
	global_store_dwordx4 v[86:87], v[64:67], off sc1
	s_cbranch_scc1 .LBB0_272

.LBB0_279:
	v_lshlrev_b64 v[86:87], 10, v[86:87]
	s_waitcnt vmcnt(1)
	v_pk_mul_f32 v[68:69], v[68:69], s[54:55] op_sel_hi:[1,0]
	v_pk_mul_f32 v[70:71], v[70:71], s[54:55] op_sel_hi:[1,0]
	v_lshl_add_u64 v[86:87], v[86:87], 2, v[80:81]
	s_waitcnt vmcnt(0) lgkmcnt(0)
	v_pk_fma_f32 v[64:65], v[64:65], v[72:73], v[68:69]
	v_pk_fma_f32 v[66:67], v[66:67], v[74:75], v[70:71]
	global_store_dwordx4 v[86:87], v[64:67], off sc1
	s_and_b64 vcc, exec, s[8:9]
	s_nop 0
	v_add_u32_e32 v64, 0x100, v92
	v_ashrrev_i32_e32 v72, 5, v64
	v_add_u32_e32 v86, s14, v72
	v_ashrrev_i32_e32 v87, 31, v86
	v_lshlrev_b64 v[64:65], 12, v[86:87]
	v_lshl_add_u64 v[64:65], v[76:77], 0, v[64:65]
	global_load_dwordx4 v[64:67], v[64:65], off
	s_nop 0
	global_load_dwordx4 v[68:71], v[78:79], off
	v_mad_u64_u32 v[72:73], s[16:17], v72, s48, v[148:149]
	ds_read_b128 v[72:75], v72 offset:32768
	s_cbranch_vccnz .LBB0_281
	v_lshlrev_b32_e32 v94, 1, v86
	v_ashrrev_i32_e32 v95, 31, v94
	v_lshl_add_u64 v[94:95], v[94:95], 2, s[30:31]
	global_load_dwordx2 v[102:103], v[94:95], off
	s_nop 0
	global_load_dwordx4 v[94:97], v[82:83], off
	global_load_dwordx4 v[98:101], v[84:85], off
	s_waitcnt vmcnt(2)
	v_pk_add_f32 v[64:65], v[64:65], v[102:103] op_sel_hi:[1,0] neg_lo:[0,1] neg_hi:[0,1]
	v_pk_add_f32 v[66:67], v[66:67], v[102:103] op_sel_hi:[1,0] neg_lo:[0,1] neg_hi:[0,1]
	v_pk_mul_f32 v[64:65], v[64:65], v[102:103] op_sel:[0,1]
	v_pk_mul_f32 v[66:67], v[66:67], v[102:103] op_sel:[0,1]
	s_waitcnt vmcnt(0)
	v_pk_fma_f32 v[64:65], v[64:65], v[94:95], v[98:99]
	v_pk_fma_f32 v[66:67], v[66:67], v[96:97], v[100:101]
.LBB0_281:
	v_lshlrev_b64 v[86:87], 10, v[86:87]
	s_waitcnt vmcnt(1)
	v_pk_mul_f32 v[64:65], v[64:65], s[54:55] op_sel_hi:[1,0]
	v_pk_mul_f32 v[66:67], v[66:67], s[54:55] op_sel_hi:[1,0]
	v_lshl_add_u64 v[86:87], v[86:87], 2, v[80:81]
	s_waitcnt vmcnt(0) lgkmcnt(0)
	v_pk_fma_f32 v[64:65], v[72:73], v[68:69], v[64:65]
	v_pk_fma_f32 v[66:67], v[74:75], v[70:71], v[66:67]
	global_store_dwordx4 v[86:87], v[64:67], off sc1
	s_and_b64 vcc, exec, s[8:9]
	s_nop 0
	v_add_u32_e32 v64, 0x200, v92
	v_ashrrev_i32_e32 v72, 5, v64
	v_add_u32_e32 v86, s14, v72
	v_ashrrev_i32_e32 v87, 31, v86
	v_lshlrev_b64 v[64:65], 12, v[86:87]
	v_lshl_add_u64 v[64:65], v[76:77], 0, v[64:65]
	global_load_dwordx4 v[64:67], v[64:65], off
	s_nop 0
	global_load_dwordx4 v[68:71], v[78:79], off
	v_mad_u64_u32 v[72:73], s[16:17], v72, s48, v[148:149]
	ds_read_b128 v[72:75], v72 offset:32768
	s_cbranch_vccnz .LBB0_283
	v_lshlrev_b32_e32 v94, 1, v86
	v_ashrrev_i32_e32 v95, 31, v94
	v_lshl_add_u64 v[94:95], v[94:95], 2, s[30:31]
	global_load_dwordx2 v[102:103], v[94:95], off
	s_nop 0
	global_load_dwordx4 v[94:97], v[82:83], off
	global_load_dwordx4 v[98:101], v[84:85], off
	s_waitcnt vmcnt(2)
	v_pk_add_f32 v[64:65], v[64:65], v[102:103] op_sel_hi:[1,0] neg_lo:[0,1] neg_hi:[0,1]
	v_pk_add_f32 v[66:67], v[66:67], v[102:103] op_sel_hi:[1,0] neg_lo:[0,1] neg_hi:[0,1]
	v_pk_mul_f32 v[64:65], v[64:65], v[102:103] op_sel:[0,1]
	v_pk_mul_f32 v[66:67], v[66:67], v[102:103] op_sel:[0,1]
	s_waitcnt vmcnt(0)
	v_pk_fma_f32 v[64:65], v[64:65], v[94:95], v[98:99]
	v_pk_fma_f32 v[66:67], v[66:67], v[96:97], v[100:101]
.LBB0_283:
	v_lshlrev_b64 v[86:87], 10, v[86:87]
	s_waitcnt vmcnt(1)
	v_pk_mul_f32 v[64:65], v[64:65], s[54:55] op_sel_hi:[1,0]
	v_pk_mul_f32 v[66:67], v[66:67], s[54:55] op_sel_hi:[1,0]
	v_lshl_add_u64 v[86:87], v[86:87], 2, v[80:81]
	s_waitcnt vmcnt(0) lgkmcnt(0)
	v_pk_fma_f32 v[64:65], v[72:73], v[68:69], v[64:65]
	v_pk_fma_f32 v[66:67], v[74:75], v[70:71], v[66:67]
	global_store_dwordx4 v[86:87], v[64:67], off sc1
	s_and_b64 vcc, exec, s[8:9]
	s_nop 0
	v_add_u32_e32 v64, 0x300, v92
	v_ashrrev_i32_e32 v72, 5, v64
	v_add_u32_e32 v86, s14, v72
	v_ashrrev_i32_e32 v87, 31, v86
	v_lshlrev_b64 v[64:65], 12, v[86:87]
	v_lshl_add_u64 v[64:65], v[76:77], 0, v[64:65]
	global_load_dwordx4 v[64:67], v[64:65], off
	s_nop 0
	global_load_dwordx4 v[68:71], v[78:79], off
	v_mad_u64_u32 v[72:73], s[16:17], v72, s48, v[148:149]
	ds_read_b128 v[72:75], v72 offset:32768
	s_cbranch_vccnz .LBB0_276
	v_lshlrev_b32_e32 v92, 1, v86
	v_ashrrev_i32_e32 v93, 31, v92
	v_lshl_add_u64 v[92:93], v[92:93], 2, s[30:31]
	global_load_dwordx2 v[100:101], v[92:93], off
	s_nop 0
	global_load_dwordx4 v[92:95], v[82:83], off
	global_load_dwordx4 v[96:99], v[84:85], off
	s_waitcnt vmcnt(2)
	v_pk_add_f32 v[64:65], v[64:65], v[100:101] op_sel_hi:[1,0] neg_lo:[0,1] neg_hi:[0,1]
	v_pk_add_f32 v[66:67], v[66:67], v[100:101] op_sel_hi:[1,0] neg_lo:[0,1] neg_hi:[0,1]
	v_pk_mul_f32 v[64:65], v[64:65], v[100:101] op_sel:[0,1]
	v_pk_mul_f32 v[66:67], v[66:67], v[100:101] op_sel:[0,1]
	s_waitcnt vmcnt(0)
	v_pk_fma_f32 v[64:65], v[64:65], v[92:93], v[96:97]
	v_pk_fma_f32 v[66:67], v[66:67], v[94:95], v[98:99]
	s_branch .LBB0_276

.LBB0_317:
	v_mov_b32_e32 v0, v254
	s_waitcnt vmcnt(0)
	s_barrier
	s_mov_b32 s49, 0xfffffc0
	v_lshrrev_b32_e32 v2, 2, v0
	v_lshrrev_b32_e32 v1, 1, v0
	v_and_b32_e32 v2, 12, v2
	v_and_or_b32 v1, v1, s49, v2
	v_and_b32_e32 v0, 0x4f, v0
	v_mul_lo_u32 v1, v1, s42
	v_lshl_add_u32 v0, v0, 1, v1
	v_cvt_pk_bf16_f32 v1, v189, s0
	ds_write_b16 v0, v1 offset:33040
	v_cvt_pk_bf16_f32 v1, v192, s0
	ds_write_b16 v0, v1 offset:33312
	v_cvt_pk_bf16_f32 v1, v193, s0
	ds_write_b16 v0, v1 offset:33584
	v_cvt_pk_bf16_f32 v1, v190, s0
	ds_write_b16 v0, v1 offset:32800
	v_cvt_pk_bf16_f32 v1, v191, s0
	ds_write_b16 v0, v1 offset:33072
	v_cvt_pk_bf16_f32 v1, v186, s0
	ds_write_b16 v0, v1 offset:33344
	v_cvt_pk_bf16_f32 v1, v187, s0
	ds_write_b16 v0, v1 offset:33616
	v_cvt_pk_bf16_f32 v1, v184, s0
	ds_write_b16 v0, v1 offset:32832
	v_cvt_pk_bf16_f32 v1, v185, s0
	ds_write_b16 v0, v1 offset:33104
	v_cvt_pk_bf16_f32 v1, v182, s0
	ds_write_b16 v0, v1 offset:33376
	v_cvt_pk_bf16_f32 v1, v183, s0
	ds_write_b16 v0, v1 offset:33648
	v_cvt_pk_bf16_f32 v1, v180, s0
	ds_write_b16 v0, v1 offset:32864
	v_cvt_pk_bf16_f32 v1, v181, s0
	ds_write_b16 v0, v1 offset:33136
	v_cvt_pk_bf16_f32 v1, v178, s0
	ds_write_b16 v0, v1 offset:33408
	v_cvt_pk_bf16_f32 v1, v179, s0
	ds_write_b16 v0, v1 offset:33680
	v_cvt_pk_bf16_f32 v1, v176, s0
	ds_write_b16 v0, v1 offset:37120
	v_cvt_pk_bf16_f32 v1, v177, s0
	ds_write_b16 v0, v1 offset:37392
	v_cvt_pk_bf16_f32 v1, v174, s0
	ds_write_b16 v0, v1 offset:37664
	v_cvt_pk_bf16_f32 v1, v175, s0
	ds_write_b16 v0, v1 offset:37936
	v_cvt_pk_bf16_f32 v1, v172, s0
	ds_write_b16 v0, v1 offset:37152
	v_cvt_pk_bf16_f32 v1, v173, s0
	ds_write_b16 v0, v1 offset:37424
	v_cvt_pk_bf16_f32 v1, v170, s0
	ds_write_b16 v0, v1 offset:37696
	v_cvt_pk_bf16_f32 v1, v171, s0
	ds_write_b16 v0, v1 offset:37968
	v_cvt_pk_bf16_f32 v1, v168, s0
	ds_write_b16 v0, v1 offset:37184
	v_cvt_pk_bf16_f32 v1, v169, s0
	ds_write_b16 v0, v1 offset:37456
	v_cvt_pk_bf16_f32 v1, v166, s0
	ds_write_b16 v0, v1 offset:37728
	v_cvt_pk_bf16_f32 v1, v167, s0
	ds_write_b16 v0, v1 offset:38000
	v_cvt_pk_bf16_f32 v1, v164, s0
	ds_write_b16 v0, v1 offset:37216
	v_cvt_pk_bf16_f32 v1, v165, s0
	ds_write_b16 v0, v1 offset:37488
	v_cvt_pk_bf16_f32 v1, v162, s0
	ds_write_b16 v0, v1 offset:37760
	v_cvt_pk_bf16_f32 v1, v163, s0
	ds_write_b16 v0, v1 offset:38032
	v_cvt_pk_bf16_f32 v1, v160, s0
	ds_write_b16 v0, v1 offset:41472
	v_cvt_pk_bf16_f32 v1, v161, s0
	ds_write_b16 v0, v1 offset:41744
	v_cvt_pk_bf16_f32 v1, v158, s0
	ds_write_b16 v0, v1 offset:42016
	v_cvt_pk_bf16_f32 v1, v159, s0
	ds_write_b16 v0, v1 offset:42288
	v_cvt_pk_bf16_f32 v1, v156, s0
	ds_write_b16 v0, v1 offset:41504
	v_cvt_pk_bf16_f32 v1, v157, s0
	ds_write_b16 v0, v1 offset:41776
	v_cvt_pk_bf16_f32 v1, v154, s0
	ds_write_b16 v0, v1 offset:42048
	v_cvt_pk_bf16_f32 v1, v155, s0
	ds_write_b16 v0, v1 offset:42320
	v_cvt_pk_bf16_f32 v1, v152, s0
	ds_write_b16 v0, v1 offset:41536
	v_cvt_pk_bf16_f32 v1, v153, s0
	ds_write_b16 v0, v1 offset:41808
	v_cvt_pk_bf16_f32 v1, v150, s0
	ds_write_b16 v0, v1 offset:42080
	v_cvt_pk_bf16_f32 v1, v151, s0
	ds_write_b16 v0, v1 offset:42352
	v_cvt_pk_bf16_f32 v1, v146, s0
	ds_write_b16 v0, v1 offset:41568
	v_cvt_pk_bf16_f32 v1, v147, s0
	ds_write_b16 v0, v1 offset:41840
	v_cvt_pk_bf16_f32 v1, v144, s0
	ds_write_b16 v0, v1 offset:42112
	v_cvt_pk_bf16_f32 v1, v145, s0
	ds_write_b16 v0, v1 offset:42384
	v_cvt_pk_bf16_f32 v1, v142, s0
	ds_write_b16 v0, v1 offset:45824
	v_cvt_pk_bf16_f32 v1, v143, s0
	ds_write_b16 v0, v1 offset:46096
	v_cvt_pk_bf16_f32 v1, v140, s0
	ds_write_b16 v0, v1 offset:46368
	v_cvt_pk_bf16_f32 v1, v141, s0
	ds_write_b16 v0, v1 offset:46640
	v_cvt_pk_bf16_f32 v1, v138, s0
	ds_write_b16 v0, v1 offset:45856
	v_cvt_pk_bf16_f32 v1, v139, s0
	ds_write_b16 v0, v1 offset:46128
	v_cvt_pk_bf16_f32 v1, v136, s0
	ds_write_b16 v0, v1 offset:46400
	v_cvt_pk_bf16_f32 v1, v137, s0
	ds_write_b16 v0, v1 offset:46672
	v_cvt_pk_bf16_f32 v1, v134, s0
	ds_write_b16 v0, v1 offset:45888
	v_cvt_pk_bf16_f32 v1, v135, s0
	ds_write_b16 v0, v1 offset:46160
	v_cvt_pk_bf16_f32 v1, v132, s0
	ds_write_b16 v0, v1 offset:46432
	v_cvt_pk_bf16_f32 v1, v133, s0
	ds_write_b16 v0, v1 offset:46704
	v_cvt_pk_bf16_f32 v1, v130, s0
	s_lshl_b64 s[14:15], s[26:27], 11
	ds_write_b16 v0, v1 offset:45920
	v_cvt_pk_bf16_f32 v1, v131, s0
	s_add_u32 s2, s93, s14
	ds_write_b16 v0, v1 offset:46192
	v_cvt_pk_bf16_f32 v1, v128, s0
	s_addc_u32 s14, s94, s15
	s_lshl_b64 s[12:13], s[12:13], 1
	v_cvt_pk_bf16_f32 v2, v188, s0
	ds_write_b16 v0, v1 offset:46464
	v_cvt_pk_bf16_f32 v1, v129, s0
	v_mov_b32_e32 v14, v254
	s_add_u32 s12, s2, s12
	ds_write_b16 v0, v2 offset:32768
	ds_write_b16 v0, v1 offset:46736
	s_waitcnt lgkmcnt(0)
	s_barrier
	s_addc_u32 s13, s14, s13
	v_lshlrev_b32_e32 v0, 4, v14
	v_ashrrev_i32_e32 v4, 4, v14
	v_and_b32_e32 v148, 0xf0, v0
	v_ashrrev_i32_e32 v5, 31, v4
	v_lshl_add_u64 v[8:9], s[12:13], 0, v[148:149]
	v_mad_u64_u32 v[0:1], s[12:13], v4, s42, v[148:149]
	v_lshlrev_b64 v[4:5], 11, v[4:5]
	v_lshl_add_u64 v[10:11], v[8:9], 0, v[4:5]
	v_add_u32_e32 v4, 0x100, v14
	ds_read_b128 v[0:3], v0 offset:32768
	v_ashrrev_i32_e32 v12, 4, v4
	v_mad_u64_u32 v[4:5], s[12:13], v12, s42, v[148:149]
	ds_read_b128 v[4:7], v4 offset:32768
	v_ashrrev_i32_e32 v13, 31, v12
	s_waitcnt lgkmcnt(1)
	global_store_dwordx4 v[10:11], v[0:3], off sc1
	s_mov_b64 s[40:41], -1
	s_and_b64 vcc, exec, s[6:7]
	v_lshlrev_b64 v[0:1], 11, v[12:13]
	v_lshl_add_u64 v[0:1], v[8:9], 0, v[0:1]
	s_waitcnt lgkmcnt(0)
	global_store_dwordx4 v[0:1], v[4:7], off sc1
	v_add_u32_e32 v0, 0x200, v14
	s_mov_b32 s2, s97
	v_ashrrev_i32_e32 v4, 4, v0
	v_ashrrev_i32_e32 v5, 31, v4
	v_mad_u64_u32 v[0:1], s[12:13], v4, s42, v[148:149]
	v_lshlrev_b64 v[4:5], 11, v[4:5]
	v_lshl_add_u64 v[10:11], v[8:9], 0, v[4:5]
	v_add_u32_e32 v4, 0x300, v14
	ds_read_b128 v[0:3], v0 offset:32768
	v_ashrrev_i32_e32 v12, 4, v4
	v_mad_u64_u32 v[4:5], s[12:13], v12, s42, v[148:149]
	ds_read_b128 v[4:7], v4 offset:32768
	v_ashrrev_i32_e32 v13, 31, v12
	s_waitcnt lgkmcnt(1)
	global_store_dwordx4 v[10:11], v[0:3], off sc1
	s_movk_i32 s98, 0x90
	s_movk_i32 s97, 0x15c0
	v_lshlrev_b64 v[0:1], 11, v[12:13]
	v_lshl_add_u64 v[0:1], v[8:9], 0, v[0:1]
	s_waitcnt lgkmcnt(0)
	global_store_dwordx4 v[0:1], v[4:7], off sc1
	v_add_u32_e32 v0, 0x400, v14
	v_mov_b32_e32 v158, v222
	v_ashrrev_i32_e32 v4, 4, v0
	v_ashrrev_i32_e32 v5, 31, v4
	v_mad_u64_u32 v[0:1], s[12:13], v4, s42, v[148:149]
	v_lshlrev_b64 v[4:5], 11, v[4:5]
	v_lshl_add_u64 v[10:11], v[8:9], 0, v[4:5]
	v_add_u32_e32 v4, 0x500, v14
	ds_read_b128 v[0:3], v0 offset:32768
	v_ashrrev_i32_e32 v12, 4, v4
	v_mad_u64_u32 v[4:5], s[12:13], v12, s42, v[148:149]
	ds_read_b128 v[4:7], v4 offset:32768
	v_ashrrev_i32_e32 v13, 31, v12
	s_waitcnt lgkmcnt(1)
	global_store_dwordx4 v[10:11], v[0:3], off sc1
	v_mov_b32_e32 v159, 1
	s_nop 0
	v_lshlrev_b64 v[0:1], 11, v[12:13]
	v_lshl_add_u64 v[0:1], v[8:9], 0, v[0:1]
	s_waitcnt lgkmcnt(0)
	global_store_dwordx4 v[0:1], v[4:7], off sc1
	v_add_u32_e32 v0, 0x600, v14
	s_nop 0
	v_ashrrev_i32_e32 v4, 4, v0
	v_ashrrev_i32_e32 v5, 31, v4
	v_mad_u64_u32 v[0:1], s[12:13], v4, s42, v[148:149]
	v_lshlrev_b64 v[4:5], 11, v[4:5]
	v_lshl_add_u64 v[10:11], v[8:9], 0, v[4:5]
	v_add_u32_e32 v4, 0x700, v14
	ds_read_b128 v[0:3], v0 offset:32768
	v_ashrrev_i32_e32 v12, 4, v4
	v_mad_u64_u32 v[4:5], s[12:13], v12, s42, v[148:149]
	ds_read_b128 v[4:7], v4 offset:32768
	v_ashrrev_i32_e32 v13, 31, v12
	s_waitcnt lgkmcnt(1)
	global_store_dwordx4 v[10:11], v[0:3], off sc1
	s_nop 1
	v_lshlrev_b64 v[0:1], 11, v[12:13]
	v_lshl_add_u64 v[0:1], v[8:9], 0, v[0:1]
	s_waitcnt lgkmcnt(0)
	global_store_dwordx4 v[0:1], v[4:7], off sc1
	s_cbranch_vccnz .LBB0_353

.LBB0_573:
	v_mov_b32_e32 v64, v254
	s_waitcnt vmcnt(0)
	s_barrier
	s_mul_i32 s13, s8, s37
	v_lshrrev_b32_e32 v66, 2, v64
	v_lshrrev_b32_e32 v65, 1, v64
	v_and_b32_e32 v66, 12, v66
	v_and_or_b32 v65, v65, s49, v66
	v_and_b32_e32 v64, 0x4f, v64
	v_mul_lo_u32 v65, v65, s42
	v_lshl_add_u32 v64, v64, 1, v65
	v_cvt_pk_bf16_f32 v65, v61, s0
	ds_write_b16 v64, v65 offset:33040
	v_cvt_pk_bf16_f32 v65, v62, s0
	ds_write_b16 v64, v65 offset:33312
	v_cvt_pk_bf16_f32 v65, v63, s0
	ds_write_b16 v64, v65 offset:33584
	v_cvt_pk_bf16_f32 v65, v56, s0
	ds_write_b16 v64, v65 offset:32800
	v_cvt_pk_bf16_f32 v65, v57, s0
	ds_write_b16 v64, v65 offset:33072
	v_cvt_pk_bf16_f32 v65, v58, s0
	ds_write_b16 v64, v65 offset:33344
	v_cvt_pk_bf16_f32 v65, v59, s0
	ds_write_b16 v64, v65 offset:33616
	v_cvt_pk_bf16_f32 v65, v52, s0
	ds_write_b16 v64, v65 offset:32832
	v_cvt_pk_bf16_f32 v65, v53, s0
	ds_write_b16 v64, v65 offset:33104
	v_cvt_pk_bf16_f32 v65, v54, s0
	ds_write_b16 v64, v65 offset:33376
	v_cvt_pk_bf16_f32 v65, v55, s0
	ds_write_b16 v64, v65 offset:33648
	v_cvt_pk_bf16_f32 v65, v48, s0
	ds_write_b16 v64, v65 offset:32864
	v_cvt_pk_bf16_f32 v65, v49, s0
	ds_write_b16 v64, v65 offset:33136
	v_cvt_pk_bf16_f32 v65, v50, s0
	ds_write_b16 v64, v65 offset:33408
	v_cvt_pk_bf16_f32 v65, v51, s0
	ds_write_b16 v64, v65 offset:33680
	v_cvt_pk_bf16_f32 v65, v44, s0
	ds_write_b16 v64, v65 offset:37120
	v_cvt_pk_bf16_f32 v65, v45, s0
	ds_write_b16 v64, v65 offset:37392
	v_cvt_pk_bf16_f32 v65, v46, s0
	ds_write_b16 v64, v65 offset:37664
	v_cvt_pk_bf16_f32 v65, v47, s0
	ds_write_b16 v64, v65 offset:37936
	v_cvt_pk_bf16_f32 v65, v40, s0
	ds_write_b16 v64, v65 offset:37152
	v_cvt_pk_bf16_f32 v65, v41, s0
	ds_write_b16 v64, v65 offset:37424
	v_cvt_pk_bf16_f32 v65, v42, s0
	ds_write_b16 v64, v65 offset:37696
	v_cvt_pk_bf16_f32 v65, v43, s0
	ds_write_b16 v64, v65 offset:37968
	v_cvt_pk_bf16_f32 v65, v36, s0
	ds_write_b16 v64, v65 offset:37184
	v_cvt_pk_bf16_f32 v65, v37, s0
	ds_write_b16 v64, v65 offset:37456
	v_cvt_pk_bf16_f32 v65, v38, s0
	ds_write_b16 v64, v65 offset:37728
	v_cvt_pk_bf16_f32 v65, v39, s0
	ds_write_b16 v64, v65 offset:38000
	v_cvt_pk_bf16_f32 v65, v32, s0
	ds_write_b16 v64, v65 offset:37216
	v_cvt_pk_bf16_f32 v65, v33, s0
	ds_write_b16 v64, v65 offset:37488
	v_cvt_pk_bf16_f32 v65, v34, s0
	ds_write_b16 v64, v65 offset:37760
	v_cvt_pk_bf16_f32 v65, v35, s0
	ds_write_b16 v64, v65 offset:38032
	v_cvt_pk_bf16_f32 v65, v28, s0
	ds_write_b16 v64, v65 offset:41472
	v_cvt_pk_bf16_f32 v65, v29, s0
	ds_write_b16 v64, v65 offset:41744
	v_cvt_pk_bf16_f32 v65, v30, s0
	ds_write_b16 v64, v65 offset:42016
	v_cvt_pk_bf16_f32 v65, v31, s0
	ds_write_b16 v64, v65 offset:42288
	v_cvt_pk_bf16_f32 v65, v20, s0
	ds_write_b16 v64, v65 offset:41504
	v_cvt_pk_bf16_f32 v65, v21, s0
	ds_write_b16 v64, v65 offset:41776
	v_cvt_pk_bf16_f32 v65, v22, s0
	ds_write_b16 v64, v65 offset:42048
	v_cvt_pk_bf16_f32 v65, v23, s0
	ds_write_b16 v64, v65 offset:42320
	v_cvt_pk_bf16_f32 v65, v12, s0
	ds_write_b16 v64, v65 offset:41536
	v_cvt_pk_bf16_f32 v65, v13, s0
	ds_write_b16 v64, v65 offset:41808
	v_cvt_pk_bf16_f32 v65, v14, s0
	ds_write_b16 v64, v65 offset:42080
	v_cvt_pk_bf16_f32 v65, v15, s0
	ds_write_b16 v64, v65 offset:42352
	v_cvt_pk_bf16_f32 v65, v8, s0
	ds_write_b16 v64, v65 offset:41568
	v_cvt_pk_bf16_f32 v65, v9, s0
	ds_write_b16 v64, v65 offset:41840
	v_cvt_pk_bf16_f32 v65, v10, s0
	ds_write_b16 v64, v65 offset:42112
	v_cvt_pk_bf16_f32 v65, v11, s0
	ds_write_b16 v64, v65 offset:42384
	v_cvt_pk_bf16_f32 v65, v4, s0
	ds_write_b16 v64, v65 offset:45824
	v_cvt_pk_bf16_f32 v65, v5, s0
	ds_write_b16 v64, v65 offset:46096
	v_cvt_pk_bf16_f32 v65, v6, s0
	ds_write_b16 v64, v65 offset:46368
	v_cvt_pk_bf16_f32 v65, v7, s0
	ds_write_b16 v64, v65 offset:46640
	v_cvt_pk_bf16_f32 v65, v0, s0
	ds_write_b16 v64, v65 offset:45856
	v_cvt_pk_bf16_f32 v65, v1, s0
	ds_write_b16 v64, v65 offset:46128
	v_cvt_pk_bf16_f32 v65, v2, s0
	ds_write_b16 v64, v65 offset:46400
	v_cvt_pk_bf16_f32 v65, v3, s0
	ds_write_b16 v64, v65 offset:46672
	v_cvt_pk_bf16_f32 v65, v24, s0
	ds_write_b16 v64, v65 offset:45888
	v_cvt_pk_bf16_f32 v65, v25, s0
	ds_write_b16 v64, v65 offset:46160
	v_cvt_pk_bf16_f32 v65, v26, s0
	ds_write_b16 v64, v65 offset:46432
	v_cvt_pk_bf16_f32 v65, v27, s0
	s_mul_hi_u32 s14, s8, s36
	ds_write_b16 v64, v65 offset:46704
	v_cvt_pk_bf16_f32 v65, v16, s0
	s_add_i32 s13, s14, s13
	s_mul_i32 s14, s9, s36
	ds_write_b16 v64, v65 offset:45920
	v_cvt_pk_bf16_f32 v65, v17, s0
	s_add_i32 s15, s13, s14
	s_mul_i32 s14, s8, s36
	ds_write_b16 v64, v65 offset:46192
	v_cvt_pk_bf16_f32 v65, v18, s0
	s_lshl_b64 s[14:15], s[14:15], 1
	v_cvt_pk_bf16_f32 v66, v60, s0
	ds_write_b16 v64, v65 offset:46464
	v_cvt_pk_bf16_f32 v65, v19, s0
	v_mov_b32_e32 v72, v254
	s_add_u32 s10, s10, s14
	ds_write_b16 v64, v66 offset:32768
	ds_write_b16 v64, v65 offset:46736
	s_waitcnt lgkmcnt(0)
	s_barrier
	s_addc_u32 s11, s11, s15
	v_lshlrev_b32_e32 v64, 4, v72
	v_and_b32_e32 v148, 0xf0, v64
	v_ashrrev_i32_e32 v70, 4, v72
	v_lshl_add_u64 v[68:69], s[10:11], 0, v[148:149]
	v_mad_u64_u32 v[64:65], s[10:11], v70, s42, v[148:149]
	ds_read_b128 v[64:67], v64 offset:32768
	v_ashrrev_i32_e32 v71, 31, v70
	v_mul_lo_u32 v73, s8, v71
	v_mul_lo_u32 v74, s9, v70
	v_mad_u64_u32 v[70:71], s[10:11], s8, v70, 0
	v_add3_u32 v71, v71, v73, v74
	v_lshl_add_u64 v[70:71], v[70:71], 1, v[68:69]
	s_waitcnt lgkmcnt(0)
	global_store_dwordx4 v[70:71], v[64:67], off sc1
	s_nop 1
	v_add_u32_e32 v64, 0x100, v72
	v_ashrrev_i32_e32 v70, 4, v64
	v_mad_u64_u32 v[64:65], s[10:11], v70, s42, v[148:149]
	ds_read_b128 v[64:67], v64 offset:32768
	v_ashrrev_i32_e32 v71, 31, v70
	v_mul_lo_u32 v73, s8, v71
	v_mul_lo_u32 v74, s9, v70
	v_mad_u64_u32 v[70:71], s[10:11], s8, v70, 0
	v_add3_u32 v71, v71, v73, v74
	v_lshl_add_u64 v[70:71], v[70:71], 1, v[68:69]
	s_waitcnt lgkmcnt(0)
	global_store_dwordx4 v[70:71], v[64:67], off sc1
	s_nop 1
	v_add_u32_e32 v64, 0x200, v72
	v_ashrrev_i32_e32 v70, 4, v64
	v_mad_u64_u32 v[64:65], s[10:11], v70, s42, v[148:149]
	ds_read_b128 v[64:67], v64 offset:32768
	v_ashrrev_i32_e32 v71, 31, v70
	v_mul_lo_u32 v73, s8, v71
	v_mul_lo_u32 v74, s9, v70
	v_mad_u64_u32 v[70:71], s[10:11], s8, v70, 0
	v_add3_u32 v71, v71, v73, v74
	v_lshl_add_u64 v[70:71], v[70:71], 1, v[68:69]
	s_waitcnt lgkmcnt(0)
	global_store_dwordx4 v[70:71], v[64:67], off sc1
	s_nop 1
	v_add_u32_e32 v64, 0x300, v72
	v_ashrrev_i32_e32 v70, 4, v64
	v_mad_u64_u32 v[64:65], s[10:11], v70, s42, v[148:149]
	ds_read_b128 v[64:67], v64 offset:32768
	v_ashrrev_i32_e32 v71, 31, v70
	v_mul_lo_u32 v73, s8, v71
	v_mul_lo_u32 v74, s9, v70
	v_mad_u64_u32 v[70:71], s[10:11], s8, v70, 0
	v_add3_u32 v71, v71, v73, v74
	v_lshl_add_u64 v[70:71], v[70:71], 1, v[68:69]
	s_waitcnt lgkmcnt(0)
	global_store_dwordx4 v[70:71], v[64:67], off sc1
	s_nop 1
	v_add_u32_e32 v64, 0x400, v72
	v_ashrrev_i32_e32 v70, 4, v64
	v_mad_u64_u32 v[64:65], s[10:11], v70, s42, v[148:149]
	ds_read_b128 v[64:67], v64 offset:32768
	v_ashrrev_i32_e32 v71, 31, v70
	v_mul_lo_u32 v73, s8, v71
	v_mul_lo_u32 v74, s9, v70
	v_mad_u64_u32 v[70:71], s[10:11], s8, v70, 0
	v_add3_u32 v71, v71, v73, v74
	v_lshl_add_u64 v[70:71], v[70:71], 1, v[68:69]
	s_waitcnt lgkmcnt(0)
	global_store_dwordx4 v[70:71], v[64:67], off sc1
	s_nop 1
	v_add_u32_e32 v64, 0x500, v72
	v_ashrrev_i32_e32 v70, 4, v64
	v_mad_u64_u32 v[64:65], s[10:11], v70, s42, v[148:149]
	ds_read_b128 v[64:67], v64 offset:32768
	v_ashrrev_i32_e32 v71, 31, v70
	v_mul_lo_u32 v73, s8, v71
	v_mul_lo_u32 v74, s9, v70
	v_mad_u64_u32 v[70:71], s[10:11], s8, v70, 0
	v_add3_u32 v71, v71, v73, v74
	v_lshl_add_u64 v[70:71], v[70:71], 1, v[68:69]
	s_waitcnt lgkmcnt(0)
	global_store_dwordx4 v[70:71], v[64:67], off sc1
	s_nop 1
	v_add_u32_e32 v64, 0x600, v72
	v_ashrrev_i32_e32 v70, 4, v64
	v_mad_u64_u32 v[64:65], s[10:11], v70, s42, v[148:149]
	ds_read_b128 v[64:67], v64 offset:32768
	v_ashrrev_i32_e32 v71, 31, v70
	v_mul_lo_u32 v73, s8, v71
	v_mul_lo_u32 v74, s9, v70
	v_mad_u64_u32 v[70:71], s[10:11], s8, v70, 0
	v_add3_u32 v71, v71, v73, v74
	v_lshl_add_u64 v[70:71], v[70:71], 1, v[68:69]
	s_waitcnt lgkmcnt(0)
	global_store_dwordx4 v[70:71], v[64:67], off sc1
	s_nop 1
	v_add_u32_e32 v64, 0x700, v72
	v_ashrrev_i32_e32 v70, 4, v64
	v_mad_u64_u32 v[64:65], s[10:11], v70, s42, v[148:149]
	ds_read_b128 v[64:67], v64 offset:32768
	v_ashrrev_i32_e32 v71, 31, v70
	v_mul_lo_u32 v72, s8, v71
	v_mul_lo_u32 v73, s9, v70
	v_mad_u64_u32 v[70:71], s[8:9], s8, v70, 0
	v_add3_u32 v71, v71, v72, v73
	v_lshl_add_u64 v[68:69], v[70:71], 1, v[68:69]
	s_waitcnt lgkmcnt(0)
	global_store_dwordx4 v[68:69], v[64:67], off sc1
	s_mov_b64 s[8:9], 0
